# GU loop B0-ahead balanced schedule (12 ds_read + 4 LDS-DMA per load segment, DMA bases in SGPRs, no VALU in load segments) + loadprio + packed SwiGLU epilogue
# speedup vs baseline: 1.0073x; 1.0010x over previous
; #define PG8_STAGE(bufoff, gbase, voff) do { _Pragma("unroll") for (int _i = 0; _i < 2; ++_i) \
;         __builtin_amdgcn_global_load_lds((const unsigned*)((const char*)(gbase) + (voff)[_i]), (PG8_LAS unsigned*)(lds + (bufoff) + ldsw + _i * 8192), 16, 0, 0); } while (0)
; #define PG8_WAIT_V(n) asm volatile("s_waitcnt vmcnt(" #n ")" ::: "memory")
; #define PG8_BAR __builtin_amdgcn_s_barrier()
; template <class Epi, class Sched, bool ALIGN_EPI = false, bool SP2 = false>
; __device__ __forceinline__ void gemm_phase(PG8_LAS unsigned char* lds, const Gemm g, const Sched& S, const Epi& E, int tid_in) {
;     ...
;     for (int i = 0; i < 2; ++i) { int R, C; stage_rc(tid * 16 + i * 8192, R, C); const int Rb = Epi::PERM ? ((R & ~31) + perm32(R & 31)) : R;
;         voffA[i] = (unsigned)(R * K + C) * 2u; voffB[i] = (unsigned)(Rb * K + C) * 2u; }
;     const size_t kstep = (size_t)(BK * 2);
;     const size_t hstep = (size_t)HALF * K * 2;
;     const size_t tstep = 2 * hstep;
;     const unsigned ldsw = (unsigned)wid * 1024u;
;     const int aoff = lds_byte(wr * 64 + fr, fq * 8), boff = lds_byte(wc * 32 + fr, fq * 8);
;     ...
;     Unit cur, nxt; int ui = 0;
;     if (!S.next(0, cur)) return;
;     f32x4 acc[2][2][4][2];
; #pragma unroll
;     for (int a = 0; a < 2; ++a)
; #pragma unroll
;         for (int b = 0; b < 2; ++b)
; #pragma unroll
;             for (int m = 0; m < 4; ++m)
; #pragma unroll
;                 for (int n = 0; n < 2; ++n) acc[a][b][m][n] = (f32x4){0.f, 0.f, 0.f, 0.f};
;     bf16x8 At[4][2], B0[2][2], B1[2][2];
;     const char* cA = (const char*)g.A + (size_t)cur.pm * tstep; const char* cB = (const char*)g.Bt + (size_t)cur.pn * tstep;
;     S.a_ready(cur);
;     if constexpr (SP2) {
;         PG8_STAGE(PG8_SB(0, 0), cB, voffB); PG8_STAGE(PG8_SB(0, 1), cB + hstep, voffB); PG8_STAGE(PG8_SA(0, 0), cA, voffA); PG8_STAGE(PG8_SA(0, 1), cA + hstep, voffA);
;         if (wr == 1) PG8_BAR;
;         PG8_WAIT_V(2); PG8_BAR;
;         PG8_STAGE(PG8_SB(1, 0), cB + kstep, voffB); PG8_STAGE(PG8_SA(1, 0), cA + kstep, voffA); PG8_STAGE(PG8_SB(1, 1), cB + hstep + kstep, voffB);
;         PG8_WAIT_V(6); PG8_BAR;
.LBB0_579:
	v_readlane_b32 s0, v255, 28
	v_readlane_b32 s1, v255, 29
	s_xor_b64 s[38:39], s[0:1], -1
	s_mov_b64 s[0:1], s[44:45]
	s_waitcnt vmcnt(0) lgkmcnt(0)
	v_mov_b64_e32 v[0:1], s[0:1]
	flat_load_dwordx2 v[4:5], v[0:1] offset:136
	v_readlane_b32 s0, v254, 23
	v_mbcnt_lo_u32_b32 v0, -1, 0
	v_mbcnt_hi_u32_b32 v0, -1, v0
	v_readlane_b32 s1, v254, 24
	v_add_u32_e32 v20, s43, v0
	s_andn2_b64 vcc, exec, s[0:1]
	v_readfirstlane_b32 s0, v20
	s_cbranch_vccnz .LBB0_595
	s_mov_b64 s[2:3], 0x13c00000
	s_waitcnt vmcnt(0) lgkmcnt(0)
	v_lshl_add_u64 v[140:141], v[4:5], 0, s[2:3]
	v_readlane_b32 s2, v255, 17
	v_readlane_b32 s3, v255, 18
	v_mov_b32_e32 v145, v129
	v_mov_b32_e32 v149, v129
	v_lshl_add_u64 v[0:1], v[4:5], 0, s[2:3]
	v_readlane_b32 s2, v255, 28
	v_readlane_b32 s3, v255, 29
	s_and_b64 s[2:3], s[2:3], exec
	s_cselect_b32 s48, 0, 0x5c00000
	v_lshl_add_u64 v[142:143], v[0:1], 0, s[48:49]
	v_lshlrev_b32_e32 v0, 4, v20
	v_add_u32_e32 v1, 0x2000, v0
	v_ashrrev_i32_e32 v2, 31, v1
	v_lshrrev_b32_e32 v2, 22, v2
	v_add_u32_e32 v2, v1, v2
	v_ashrrev_i32_e32 v14, 10, v2
	v_mul_i32_i24_e32 v2, 0x400, v14
	v_sub_u32_e32 v1, v1, v2
	v_lshrrev_b32_e32 v2, 4, v1
	v_bitop3_b32 v1, v2, v1, 32 bitop3:0x6c
	v_ashrrev_i32_e32 v2, 31, v1
	v_lshrrev_b32_e32 v2, 26, v2
	v_add_u32_e32 v2, v1, v2
	v_lshlrev_b32_e32 v3, 3, v14
	v_ashrrev_i32_e32 v15, 6, v2
	v_and_b32_e32 v3, -16, v3
	v_add_u32_e32 v3, v15, v3
	v_and_b32_e32 v6, 3, v15
	s_mov_b32 s2, 0xfffe0
	v_lshrrev_b32_e32 v7, 2, v3
	v_lshlrev_b32_e32 v8, 1, v3
	v_and_b32_e32 v2, 0xc0, v2
	v_and_or_b32 v6, v3, s2, v6
	v_and_b32_e32 v7, 4, v7
	v_and_b32_e32 v8, 24, v8
	v_sub_u32_e32 v1, v1, v2
	v_or3_b32 v6, v6, v7, v8
	v_lshlrev_b32_e32 v7, 5, v14
	v_ashrrev_i16_sdwa v1, v170, sext(v1) dst_sel:DWORD dst_unused:UNUSED_PAD src0_sel:DWORD src1_sel:BYTE_0
	v_and_b32_e32 v7, 32, v7
	v_bfe_i32 v16, v1, 0, 16
	v_add_lshl_u32 v1, v7, v16, 1
	v_lshl_add_u32 v144, v6, 12, v1
	v_lshl_add_u32 v146, v3, 12, v1
	v_bfe_i32 v1, v20, 27, 1
	v_lshrrev_b32_e32 v1, 22, v1
	v_add_u32_e32 v1, v0, v1
	v_and_b32_e32 v1, 0xfffffc00, v1
	v_sub_u32_e32 v0, v0, v1
	v_lshrrev_b32_e32 v1, 4, v0
	v_ashrrev_i32_e32 v2, 31, v20
	v_bitop3_b32 v0, v1, v0, 32 bitop3:0x6c
	v_lshrrev_b32_e32 v2, 26, v2
	v_ashrrev_i32_e32 v1, 31, v0
	v_add_u32_e32 v2, v20, v2
	v_lshrrev_b32_e32 v1, 26, v1
	v_ashrrev_i32_e32 v18, 6, v2
	v_add_u32_e32 v1, v0, v1
	v_lshlrev_b32_e32 v2, 3, v18
	v_ashrrev_i32_e32 v17, 6, v1
	v_and_b32_e32 v2, -16, v2
	v_add_u32_e32 v2, v17, v2
	v_and_b32_e32 v3, 3, v17
	v_lshrrev_b32_e32 v6, 2, v2
	v_lshlrev_b32_e32 v7, 1, v2
	v_and_b32_e32 v1, 0xc0, v1
	v_and_or_b32 v3, v2, s2, v3
	v_and_b32_e32 v6, 4, v6
	v_and_b32_e32 v7, 24, v7
	v_sub_u32_e32 v0, v0, v1
	v_or3_b32 v3, v3, v6, v7
	v_lshlrev_b32_e32 v6, 5, v18
	v_ashrrev_i16_sdwa v0, v170, sext(v0) dst_sel:DWORD dst_unused:UNUSED_PAD src0_sel:DWORD src1_sel:BYTE_0
	s_ashr_i32 s1, s0, 6
	v_and_b32_e32 v6, 32, v6
	v_bfe_i32 v19, v0, 0, 16
	v_readlane_b32 s2, v254, 42
	s_lshl_b32 s14, s1, 10
	v_add_lshl_u32 v0, v6, v19, 1
	v_readlane_b32 s3, v254, 43
	v_lshl_add_u32 v128, v3, 12, v0
	v_lshl_add_u32 v148, v2, 12, v0
	v_lshl_add_u64 v[0:1], v[142:143], 0, s[2:3]
	s_add_i32 s15, s14, 0
	s_add_i32 m0, s15, 0x10000
	v_lshl_add_u64 v[6:7], v[0:1], 0, v[128:129]
	global_load_lds_dwordx4 v[6:7], off
	v_lshl_add_u64 v[8:9], v[0:1], 0, v[144:145]
	s_add_i32 m0, s15, 0x12000
	v_lshl_add_u64 v[2:3], v[0:1], 0, s[98:99]
	global_load_lds_dwordx4 v[8:9], off
	s_add_i32 m0, s15, 0x14000
	v_lshl_add_u64 v[10:11], v[2:3], 0, v[128:129]
	v_readlane_b32 s2, v254, 40
	global_load_lds_dwordx4 v[10:11], off
	v_lshl_add_u64 v[2:3], v[2:3], 0, v[144:145]
	s_add_i32 m0, s15, 0x16000
	v_readlane_b32 s3, v254, 41
	global_load_lds_dwordx4 v[2:3], off
	s_nop 0
	v_lshl_add_u64 v[2:3], v[140:141], 0, s[2:3]
	v_lshl_add_u64 v[10:11], v[2:3], 0, v[148:149]
	s_mov_b32 m0, s15
	v_mov_b32_e32 v147, v129
	s_add_i32 s16, s15, 0x2000
	global_load_lds_dwordx4 v[10:11], off
	v_lshl_add_u64 v[12:13], v[2:3], 0, v[146:147]
	s_mov_b32 m0, s16
	v_lshl_add_u64 v[22:23], v[2:3], 0, s[98:99]
	s_add_i32 s17, s15, 0x4000
	global_load_lds_dwordx4 v[12:13], off
	v_lshl_add_u64 v[24:25], v[22:23], 0, v[148:149]
	s_mov_b32 m0, s17
	s_add_i32 s18, s15, 0x6000
	global_load_lds_dwordx4 v[24:25], off
	v_lshl_add_u64 v[22:23], v[22:23], 0, v[146:147]
	s_mov_b32 m0, s18
	s_ashr_i32 s2, s0, 8
	global_load_lds_dwordx4 v[22:23], off
	s_add_i32 m0, s15, 0x18000
	v_lshl_add_u64 v[248:249], v[6:7], 0, s[70:71]
	global_load_lds_dwordx4 v[248:249], off
	s_add_i32 m0, s15, 0x1a000
	v_lshl_add_u64 v[248:249], v[8:9], 0, s[70:71]
	global_load_lds_dwordx4 v[248:249], off
	s_cmp_eq_u32 s2, 1
	s_cselect_b64 s[6:7], -1, 0
	s_cmp_lg_u32 s2, 1
	s_cbranch_scc1 .LBB0_582
	s_barrier
.LBB0_582:
	v_lshl_add_u64 v[150:151], v[4:5], 0, s[40:41]
	v_lshrrev_b32_e32 v5, 1, v20
	v_and_b32_e32 v21, 24, v5
	v_and_b32_e32 v4, 15, v20
	v_lshlrev_b32_e32 v5, 1, v21
	v_lshl_or_b32 v163, s2, 6, v4
	v_lshl_or_b32 v4, v4, 6, v5
	v_lshlrev_b32_e32 v5, 2, v20
	s_lshl_b32 s2, s2, 13
	v_and_b32_e32 v5, 32, v5
	s_lshl_b32 s1, s1, 5
	v_bitop3_b32 v20, v4, s2, v5 bitop3:0xde
	s_and_b32 s2, s1, 0x60
	s_lshl_b32 s1, s2, 7
	v_bitop3_b32 v168, v4, s1, v5 bitop3:0xde
	v_add_u32_e32 v173, 0x10000, v168
	s_waitcnt vmcnt(4)
	s_barrier
	s_add_i32 s19, s15, 0x8000
	v_lshl_add_u64 v[4:5], v[10:11], 0, s[70:71]
	s_mov_b32 m0, s19
	s_add_i32 s1, s15, 0xa000
	global_load_lds_dwordx4 v[4:5], off
	v_lshl_add_u64 v[4:5], v[12:13], 0, s[70:71]
	s_mov_b32 m0, s1
	v_or_b32_e32 v169, s2, v21
	global_load_lds_dwordx4 v[4:5], off
	v_lshl_add_u64 v[4:5], v[0:1], 0, s[86:87]
	s_add_i32 m0, s15, 0x1c000
	v_lshl_add_u64 v[6:7], v[4:5], 0, v[128:129]
	global_load_lds_dwordx4 v[6:7], off
	v_lshl_add_u64 v[4:5], v[4:5], 0, v[144:145]
	s_add_i32 m0, s15, 0x1e000
	s_cmpk_lt_u32 s0, 0x100
	global_load_lds_dwordx4 v[4:5], off
	v_lshlrev_b32_e32 v4, 15, v14
	v_and_b32_e32 v4, 0xffff0000, v4
	v_lshl_add_u32 v4, v15, 12, v4
	v_and_b32_e32 v5, 1, v14
	v_lshl_or_b32 v4, v5, 6, v4
	v_lshl_add_u32 v152, v16, 1, v4
	v_lshlrev_b32_e32 v4, 15, v18
	v_and_b32_e32 v4, 0xffff0000, v4
	s_waitcnt vmcnt(8)
	v_lshl_add_u32 v4, v17, 12, v4
	v_and_b32_e32 v5, 1, v18
	v_lshl_or_b32 v4, v5, 6, v4
	v_readlane_b32 s2, v254, 38
	s_cselect_b64 s[8:9], -1, 0
	v_mov_b32_e32 v153, v129
	v_lshl_add_u32 v154, v19, 1, v4
	v_mov_b32_e32 v155, v129
	s_mov_b32 s0, 0
	v_add_u32_e32 v175, 0, v20
	v_readlane_b32 s20, v254, 37
	s_mov_b32 s21, s2
	s_barrier
	ds_read_b128 v[176:179], v173
	ds_read_b128 v[180:183], v173 offset:1024
	ds_read_b128 v[184:187], v173 offset:2048
	ds_read_b128 v[188:191], v173 offset:3072
	s_waitcnt lgkmcnt(0)
	s_barrier
	s_barrier
	v_readlane_b32 s3, v254, 39
	s_branch .LBB0_585

; #define PG8_STAGE(bufoff, gbase, voff) do { _Pragma("unroll") for (int _i = 0; _i < 2; ++_i) \
;         __builtin_amdgcn_global_load_lds((const unsigned*)((const char*)(gbase) + (voff)[_i]), (PG8_LAS unsigned*)(lds + (bufoff) + ldsw + _i * 8192), 16, 0, 0); } while (0)
; #define PG8_LDA(dst, b, h) do { _Pragma("unroll") for (int m = 0; m < 4; ++m) _Pragma("unroll") for (int k = 0; k < 2; ++k) dst[m][k] = *(const PG8_LAS bf16x8*)(lds + PG8_SA(b, h) + aoff + m * 2048 + k * 1024); } while (0)
; #define PG8_LDB(dst, b, h) do { _Pragma("unroll") for (int n = 0; n < 2; ++n) _Pragma("unroll") for (int k = 0; k < 2; ++k) dst[n][k] = *(const PG8_LAS bf16x8*)(lds + PG8_SB(b, h) + boff + n * 2048 + k * 1024); } while (0)
; #define PG8_WAIT_V(n) asm volatile("s_waitcnt vmcnt(" #n ")" ::: "memory")
; #define PG8_WAIT_L(n) asm volatile("s_waitcnt lgkmcnt(" #n ")" ::: "memory")
; #define PG8_BAR __builtin_amdgcn_s_barrier()
; template <class Epi, class Sched, bool ALIGN_EPI = false, bool SP2 = false>
; __device__ __forceinline__ void gemm_phase(PG8_LAS unsigned char* lds, const Gemm g, const Sched& S, const Epi& E, int tid_in) {
;     ...
;         const bool has_next = S.next(ui + 1, nxt);
;         const char* nA = has_next ? (const char*)g.A + (size_t)nxt.pm * tstep : cA; const char* nB = has_next ? (const char*)g.Bt + (size_t)nxt.pn * tstep : cB;
;         for (int t = 0; t < nt; t += 2) {
;             const bool last = (t == nt - 2);
;             const char* a1 = cA + (size_t)(t + 1) * kstep;
;             const char* a2 = last ? nA : cA + (size_t)(t + 2) * kstep; const char* b2 = last ? nB : cB + (size_t)(t + 2) * kstep;
;             const char* a3 = a2 + kstep; const char* b3 = b2 + kstep;
;             if (last && has_next) S.a_ready(nxt);
;             if constexpr (SP2) {
;             PG8_LDB(B0, 0, 0); PG8_LDB(B1, 0, 1); PG8_SCHED; PG8_LDA(At, 0, 0); PG8_STAGE(PG8_SA(1, 1), a1 + hstep, voffA);
;             PG8_WAIT_V(8); PG8_WAIT_L(0); PG8_BAR; PG8_MMA(0, 0, At, B0); PG8_MMA(0, 1, At, B1); PG8_BAR; PG8_SCHED;
;     ...
;         for (int a = 0; a < 2; ++a)
; #pragma unroll
;             for (int b = 0; b < 2; ++b)
; #pragma unroll
;                 for (int m = 0; m < 4; ++m)
; #pragma unroll
;                     for (int n = 0; n < 2; ++n) acc[a][b][m][n] = (f32x4){0.f, 0.f, 0.f, 0.f};
;         cur = nxt; cA = nA; cB = nB; ++ui;
.LBB0_587:
	s_ashr_i32 s13, s12, 31
	s_lshl_b64 s[2:3], s[12:13], 20
	s_ashr_i32 s11, s10, 31
	v_lshl_add_u64 v[156:157], v[140:141], 0, s[2:3]
	s_lshl_b64 s[2:3], s[10:11], 20
	v_lshl_add_u64 v[158:159], v[142:143], 0, s[2:3]
	v_cndmask_b32_e64 v162, v0, v158, s[4:5]
	v_lshl_add_u64 v[164:165], v[0:1], 0, s[82:83]
	v_mov_b32_e32 v0, 0
	v_cndmask_b32_e64 v131, v3, v157, s[4:5]
	v_cndmask_b32_e64 v160, v2, v156, s[4:5]
	v_cndmask_b32_e64 v161, v1, v159, s[4:5]
	v_lshl_add_u64 v[166:167], v[2:3], 0, s[86:87]
	s_mov_b32 s2, -2
	v_readfirstlane_b32 s100, v166
	v_readfirstlane_b32 s101, v167
	v_readfirstlane_b32 s18, v164
	v_readfirstlane_b32 s19, v165
	s_nop 1
	s_add_u32 s16, s100, 0xfff80080
	s_addc_u32 s17, s101, -1
	v_mov_b32_e32 v1, v0
	v_mov_b32_e32 v2, v0
	v_mov_b32_e32 v3, v0
	v_mov_b32_e32 v8, v0
	v_mov_b32_e32 v9, v0
	v_mov_b32_e32 v10, v0
	v_mov_b32_e32 v11, v0
	v_mov_b32_e32 v16, v0
	v_mov_b32_e32 v17, v0
	v_mov_b32_e32 v18, v0
	v_mov_b32_e32 v19, v0
	v_mov_b32_e32 v24, v0
	v_mov_b32_e32 v25, v0
	v_mov_b32_e32 v26, v0
	v_mov_b32_e32 v27, v0
	v_mov_b32_e32 v32, v0
	v_mov_b32_e32 v33, v0
	v_mov_b32_e32 v34, v0
	v_mov_b32_e32 v35, v0
	v_mov_b32_e32 v40, v0
	v_mov_b32_e32 v41, v0
	v_mov_b32_e32 v42, v0
	v_mov_b32_e32 v43, v0
	v_mov_b32_e32 v48, v0
	v_mov_b32_e32 v49, v0
	v_mov_b32_e32 v50, v0
	v_mov_b32_e32 v51, v0
	v_mov_b32_e32 v56, v0
	v_mov_b32_e32 v57, v0
	v_mov_b32_e32 v58, v0
	v_mov_b32_e32 v59, v0
	v_mov_b32_e32 v4, v0
	v_mov_b32_e32 v5, v0
	v_mov_b32_e32 v6, v0
	v_mov_b32_e32 v7, v0
	v_mov_b32_e32 v12, v0
	v_mov_b32_e32 v13, v0
	v_mov_b32_e32 v14, v0
	v_mov_b32_e32 v15, v0
	v_mov_b32_e32 v20, v0
	v_mov_b32_e32 v21, v0
	v_mov_b32_e32 v22, v0
	v_mov_b32_e32 v23, v0
	v_mov_b32_e32 v28, v0
	v_mov_b32_e32 v29, v0
	v_mov_b32_e32 v30, v0
	v_mov_b32_e32 v31, v0
	v_mov_b32_e32 v36, v0
	v_mov_b32_e32 v37, v0
	v_mov_b32_e32 v38, v0
	v_mov_b32_e32 v39, v0
	v_mov_b32_e32 v44, v0
	v_mov_b32_e32 v45, v0
	v_mov_b32_e32 v46, v0
	v_mov_b32_e32 v47, v0
	v_mov_b32_e32 v52, v0
	v_mov_b32_e32 v53, v0
	v_mov_b32_e32 v54, v0
	v_mov_b32_e32 v55, v0
	v_mov_b32_e32 v60, v0
	v_mov_b32_e32 v61, v0
	v_mov_b32_e32 v62, v0
	v_mov_b32_e32 v63, v0
	v_mov_b32_e32 v64, v0
	v_mov_b32_e32 v65, v0
	v_mov_b32_e32 v66, v0
	v_mov_b32_e32 v67, v0
	v_mov_b32_e32 v72, v0
	v_mov_b32_e32 v73, v0
	v_mov_b32_e32 v74, v0
	v_mov_b32_e32 v75, v0
	v_mov_b32_e32 v80, v0
	v_mov_b32_e32 v81, v0
	v_mov_b32_e32 v82, v0
	v_mov_b32_e32 v83, v0
	v_mov_b32_e32 v88, v0
	v_mov_b32_e32 v89, v0
	v_mov_b32_e32 v90, v0
	v_mov_b32_e32 v91, v0
	v_mov_b32_e32 v96, v0
	v_mov_b32_e32 v97, v0
	v_mov_b32_e32 v98, v0
	v_mov_b32_e32 v99, v0
	v_mov_b32_e32 v104, v0
	v_mov_b32_e32 v105, v0
	v_mov_b32_e32 v106, v0
	v_mov_b32_e32 v107, v0
	v_mov_b32_e32 v112, v0
	v_mov_b32_e32 v113, v0
	v_mov_b32_e32 v114, v0
	v_mov_b32_e32 v115, v0
	v_mov_b32_e32 v120, v0
	v_mov_b32_e32 v121, v0
	v_mov_b32_e32 v122, v0
	v_mov_b32_e32 v123, v0
	v_mov_b32_e32 v68, v0
	v_mov_b32_e32 v69, v0
	v_mov_b32_e32 v70, v0
	v_mov_b32_e32 v71, v0
	v_mov_b32_e32 v76, v0
	v_mov_b32_e32 v77, v0
	v_mov_b32_e32 v78, v0
	v_mov_b32_e32 v79, v0
	v_mov_b32_e32 v84, v0
	v_mov_b32_e32 v85, v0
	v_mov_b32_e32 v86, v0
	v_mov_b32_e32 v87, v0
	v_mov_b32_e32 v92, v0
	v_mov_b32_e32 v93, v0
	v_mov_b32_e32 v94, v0
	v_mov_b32_e32 v95, v0
	v_mov_b32_e32 v100, v0
	v_mov_b32_e32 v101, v0
	v_mov_b32_e32 v102, v0
	v_mov_b32_e32 v103, v0
	v_mov_b32_e32 v108, v0
	v_mov_b32_e32 v109, v0
	v_mov_b32_e32 v110, v0
	v_mov_b32_e32 v111, v0
	v_mov_b32_e32 v116, v0
	v_mov_b32_e32 v117, v0
	v_mov_b32_e32 v118, v0
	v_mov_b32_e32 v119, v0
	v_mov_b32_e32 v124, v0
	v_mov_b32_e32 v125, v0
	v_mov_b32_e32 v126, v0
	v_mov_b32_e32 v127, v0
	s_setprio 1
.LBB0_588:
	ds_read_b128 v[192:195], v173 offset:16384
	ds_read_b128 v[196:199], v173 offset:17408
	ds_read_b128 v[200:203], v173 offset:18432
	ds_read_b128 v[204:207], v173 offset:19456
	ds_read_b128 v[208:211], v175
	ds_read_b128 v[212:215], v175 offset:1024
	ds_read_b128 v[216:219], v175 offset:2048
	ds_read_b128 v[220:223], v175 offset:3072
	ds_read_b128 v[224:227], v175 offset:4096
	ds_read_b128 v[228:231], v175 offset:5120
	ds_read_b128 v[232:235], v175 offset:6144
	ds_read_b128 v[236:239], v175 offset:7168
	s_add_i32 m0, s14, 0xc000
	s_nop 0
	global_load_lds_dwordx4 v154, s[100:101]
	s_add_i32 m0, s14, 0xe000
	s_nop 0
	global_load_lds_dwordx4 v152, s[100:101]
	s_add_i32 m0, s14, 0x10000
	s_nop 0
	global_load_lds_dwordx4 v128, s[18:19]
	s_add_i32 m0, s14, 0x12000
	s_nop 0
	global_load_lds_dwordx4 v144, s[18:19]
	s_setprio 0
	s_waitcnt vmcnt(8) lgkmcnt(0)
	s_barrier
; #define PG8_STAGE(bufoff, gbase, voff) do { _Pragma("unroll") for (int _i = 0; _i < 2; ++_i) \
;         __builtin_amdgcn_global_load_lds((const unsigned*)((const char*)(gbase) + (voff)[_i]), (PG8_LAS unsigned*)(lds + (bufoff) + ldsw + _i * 8192), 16, 0, 0); } while (0)
; #define PG8_LDA(dst, b, h) do { _Pragma("unroll") for (int m = 0; m < 4; ++m) _Pragma("unroll") for (int k = 0; k < 2; ++k) dst[m][k] = *(const PG8_LAS bf16x8*)(lds + PG8_SA(b, h) + aoff + m * 2048 + k * 1024); } while (0)
; #define PG8_MMA(ai, bj, At, Bt) do { __builtin_amdgcn_s_setprio(1); _Pragma("unroll") for (int m = 0; m < 4; ++m) _Pragma("unroll") for (int n = 0; n < 2; ++n) _Pragma("unroll") for (int k = 0; k < 2; ++k) \
;         acc[ai][bj][m][n] = __builtin_amdgcn_mfma_f32_16x16x32_bf16(Bt[n][k], At[m][k], acc[ai][bj][m][n], 0, 0, 0); __builtin_amdgcn_s_setprio(0); } while (0)
; #define PG8_WAIT_V(n) asm volatile("s_waitcnt vmcnt(" #n ")" ::: "memory")
; #define PG8_WAIT_L(n) asm volatile("s_waitcnt lgkmcnt(" #n ")" ::: "memory")
; #define PG8_BAR __builtin_amdgcn_s_barrier()
; #define PG8_SCHED __builtin_amdgcn_sched_barrier(0)
; template <class Epi, class Sched, bool ALIGN_EPI = false, bool SP2 = false>
; __device__ __forceinline__ void gemm_phase(PG8_LAS unsigned char* lds, const Gemm g, const Sched& S, const Epi& E, int tid_in) {
;     ...
;             PG8_WAIT_V(8); PG8_WAIT_L(0); PG8_BAR; PG8_MMA(0, 0, At, B0); PG8_MMA(0, 1, At, B1); PG8_BAR; PG8_SCHED;
;             PG8_LDA(At, 0, 1); PG8_STAGE(PG8_SB(0, 0), b2, voffB); PG8_STAGE(PG8_SB(0, 1), b2 + hstep, voffB); PG8_STAGE(PG8_SA(0, 0), a2, voffA);
;             PG8_WAIT_V(8); PG8_WAIT_L(0); PG8_BAR; PG8_MMA(1, 0, At, B0); PG8_MMA(1, 1, At, B1); PG8_BAR; PG8_SCHED;
	v_mfma_f32_16x16x32_bf16 v[124:127], v[176:179], v[208:211], v[124:127]
	v_mfma_f32_16x16x32_bf16 v[116:119], v[184:187], v[208:211], v[116:119]
	v_mfma_f32_16x16x32_bf16 v[108:111], v[176:179], v[216:219], v[108:111]
	v_mfma_f32_16x16x32_bf16 v[100:103], v[184:187], v[216:219], v[100:103]
	v_mfma_f32_16x16x32_bf16 v[92:95], v[176:179], v[224:227], v[92:95]
	v_mfma_f32_16x16x32_bf16 v[84:87], v[184:187], v[224:227], v[84:87]
	v_mfma_f32_16x16x32_bf16 v[76:79], v[176:179], v[232:235], v[76:79]
	v_mfma_f32_16x16x32_bf16 v[68:71], v[184:187], v[232:235], v[68:71]
	v_mfma_f32_16x16x32_bf16 v[124:127], v[180:183], v[212:215], v[124:127]
	v_mfma_f32_16x16x32_bf16 v[116:119], v[188:191], v[212:215], v[116:119]
	v_mfma_f32_16x16x32_bf16 v[108:111], v[180:183], v[220:223], v[108:111]
	v_mfma_f32_16x16x32_bf16 v[100:103], v[188:191], v[220:223], v[100:103]
	v_mfma_f32_16x16x32_bf16 v[92:95], v[180:183], v[228:231], v[92:95]
	v_mfma_f32_16x16x32_bf16 v[84:87], v[188:191], v[228:231], v[84:87]
	v_mfma_f32_16x16x32_bf16 v[76:79], v[180:183], v[236:239], v[76:79]
	v_mfma_f32_16x16x32_bf16 v[68:71], v[188:191], v[236:239], v[68:71]
	v_mfma_f32_16x16x32_bf16 v[120:123], v[192:195], v[208:211], v[120:123]
	v_mfma_f32_16x16x32_bf16 v[112:115], v[200:203], v[208:211], v[112:115]
	v_mfma_f32_16x16x32_bf16 v[104:107], v[192:195], v[216:219], v[104:107]
	v_mfma_f32_16x16x32_bf16 v[96:99], v[200:203], v[216:219], v[96:99]
	v_mfma_f32_16x16x32_bf16 v[88:91], v[192:195], v[224:227], v[88:91]
	v_mfma_f32_16x16x32_bf16 v[80:83], v[200:203], v[224:227], v[80:83]
	v_mfma_f32_16x16x32_bf16 v[72:75], v[192:195], v[232:235], v[72:75]
	v_mfma_f32_16x16x32_bf16 v[64:67], v[200:203], v[232:235], v[64:67]
	v_mfma_f32_16x16x32_bf16 v[120:123], v[196:199], v[212:215], v[120:123]
	v_mfma_f32_16x16x32_bf16 v[112:115], v[204:207], v[212:215], v[112:115]
	v_mfma_f32_16x16x32_bf16 v[104:107], v[196:199], v[220:223], v[104:107]
	v_mfma_f32_16x16x32_bf16 v[96:99], v[204:207], v[220:223], v[96:99]
	v_mfma_f32_16x16x32_bf16 v[88:91], v[196:199], v[228:231], v[88:91]
	v_mfma_f32_16x16x32_bf16 v[80:83], v[204:207], v[228:231], v[80:83]
	v_mfma_f32_16x16x32_bf16 v[72:75], v[196:199], v[236:239], v[72:75]
	v_mfma_f32_16x16x32_bf16 v[64:67], v[204:207], v[236:239], v[64:67]
	s_barrier
	s_setprio 1
	ds_read_b128 v[208:211], v175 offset:16384
	ds_read_b128 v[212:215], v175 offset:17408
	ds_read_b128 v[216:219], v175 offset:18432
	ds_read_b128 v[220:223], v175 offset:19456
	ds_read_b128 v[224:227], v175 offset:20480
	ds_read_b128 v[228:231], v175 offset:21504
	ds_read_b128 v[232:235], v175 offset:22528
	ds_read_b128 v[236:239], v175 offset:23552
	ds_read_b128 v[240:243], v173 offset:32768
	ds_read_b128 v[244:247], v173 offset:33792
	ds_read_b128 v[248:251], v173 offset:34816
	ds_read_b128 v[164:167], v173 offset:35840
	s_add_i32 m0, s14, 0x14000
	s_add_u32 s100, s18, 0x80000
	s_addc_u32 s101, s19, 0
	global_load_lds_dwordx4 v128, s[100:101]
	s_add_i32 m0, s14, 0x16000
	s_nop 0
	global_load_lds_dwordx4 v144, s[100:101]
	s_add_i32 m0, s14, 0x0
	s_nop 0
	global_load_lds_dwordx4 v148, s[16:17]
	s_add_i32 m0, s14, 0x2000
	s_nop 0
	global_load_lds_dwordx4 v146, s[16:17]
	s_setprio 0
	s_waitcnt vmcnt(8) lgkmcnt(0)
	s_barrier
	v_mfma_f32_16x16x32_bf16 v[60:63], v[176:179], v[208:211], v[60:63]
	v_mfma_f32_16x16x32_bf16 v[52:55], v[184:187], v[208:211], v[52:55]
	v_mfma_f32_16x16x32_bf16 v[44:47], v[176:179], v[216:219], v[44:47]
	v_mfma_f32_16x16x32_bf16 v[36:39], v[184:187], v[216:219], v[36:39]
	v_mfma_f32_16x16x32_bf16 v[28:31], v[176:179], v[224:227], v[28:31]
	v_mfma_f32_16x16x32_bf16 v[20:23], v[184:187], v[224:227], v[20:23]
	v_mfma_f32_16x16x32_bf16 v[12:15], v[176:179], v[232:235], v[12:15]
	v_mfma_f32_16x16x32_bf16 v[4:7], v[184:187], v[232:235], v[4:7]
	v_mfma_f32_16x16x32_bf16 v[60:63], v[180:183], v[212:215], v[60:63]
	v_mfma_f32_16x16x32_bf16 v[52:55], v[188:191], v[212:215], v[52:55]
	v_mfma_f32_16x16x32_bf16 v[44:47], v[180:183], v[220:223], v[44:47]
	v_mfma_f32_16x16x32_bf16 v[36:39], v[188:191], v[220:223], v[36:39]
	v_mfma_f32_16x16x32_bf16 v[28:31], v[180:183], v[228:231], v[28:31]
	v_mfma_f32_16x16x32_bf16 v[20:23], v[188:191], v[228:231], v[20:23]
	v_mfma_f32_16x16x32_bf16 v[12:15], v[180:183], v[236:239], v[12:15]
	v_mfma_f32_16x16x32_bf16 v[4:7], v[188:191], v[236:239], v[4:7]
	v_mfma_f32_16x16x32_bf16 v[56:59], v[192:195], v[208:211], v[56:59]
	v_mfma_f32_16x16x32_bf16 v[48:51], v[200:203], v[208:211], v[48:51]
	v_mfma_f32_16x16x32_bf16 v[40:43], v[192:195], v[216:219], v[40:43]
	v_mfma_f32_16x16x32_bf16 v[32:35], v[200:203], v[216:219], v[32:35]
	v_mfma_f32_16x16x32_bf16 v[24:27], v[192:195], v[224:227], v[24:27]
	v_mfma_f32_16x16x32_bf16 v[16:19], v[200:203], v[224:227], v[16:19]
	v_mfma_f32_16x16x32_bf16 v[8:11], v[192:195], v[232:235], v[8:11]
	v_mfma_f32_16x16x32_bf16 v[0:3], v[200:203], v[232:235], v[0:3]
	v_mfma_f32_16x16x32_bf16 v[56:59], v[196:199], v[212:215], v[56:59]
	v_mfma_f32_16x16x32_bf16 v[48:51], v[204:207], v[212:215], v[48:51]
	v_mfma_f32_16x16x32_bf16 v[40:43], v[196:199], v[220:223], v[40:43]
	v_mfma_f32_16x16x32_bf16 v[32:35], v[204:207], v[220:223], v[32:35]
	v_mfma_f32_16x16x32_bf16 v[24:27], v[196:199], v[228:231], v[24:27]
	v_mfma_f32_16x16x32_bf16 v[16:19], v[204:207], v[228:231], v[16:19]
	v_mfma_f32_16x16x32_bf16 v[8:11], v[196:199], v[236:239], v[8:11]
	v_mfma_f32_16x16x32_bf16 v[0:3], v[204:207], v[236:239], v[0:3]
	s_barrier
; #define PG8_STAGE(bufoff, gbase, voff) do { _Pragma("unroll") for (int _i = 0; _i < 2; ++_i) \
;         __builtin_amdgcn_global_load_lds((const unsigned*)((const char*)(gbase) + (voff)[_i]), (PG8_LAS unsigned*)(lds + (bufoff) + ldsw + _i * 8192), 16, 0, 0); } while (0)
; #define PG8_LDA(dst, b, h) do { _Pragma("unroll") for (int m = 0; m < 4; ++m) _Pragma("unroll") for (int k = 0; k < 2; ++k) dst[m][k] = *(const PG8_LAS bf16x8*)(lds + PG8_SA(b, h) + aoff + m * 2048 + k * 1024); } while (0)
; #define PG8_LDB(dst, b, h) do { _Pragma("unroll") for (int n = 0; n < 2; ++n) _Pragma("unroll") for (int k = 0; k < 2; ++k) dst[n][k] = *(const PG8_LAS bf16x8*)(lds + PG8_SB(b, h) + boff + n * 2048 + k * 1024); } while (0)
; #define PG8_MMA(ai, bj, At, Bt) do { __builtin_amdgcn_s_setprio(1); _Pragma("unroll") for (int m = 0; m < 4; ++m) _Pragma("unroll") for (int n = 0; n < 2; ++n) _Pragma("unroll") for (int k = 0; k < 2; ++k) \
;         acc[ai][bj][m][n] = __builtin_amdgcn_mfma_f32_16x16x32_bf16(Bt[n][k], At[m][k], acc[ai][bj][m][n], 0, 0, 0); __builtin_amdgcn_s_setprio(0); } while (0)
; #define PG8_WAIT_V(n) asm volatile("s_waitcnt vmcnt(" #n ")" ::: "memory")
; #define PG8_WAIT_L(n) asm volatile("s_waitcnt lgkmcnt(" #n ")" ::: "memory")
; #define PG8_BAR __builtin_amdgcn_s_barrier()
; template <class Epi, class Sched, bool ALIGN_EPI = false, bool SP2 = false>
; __device__ __forceinline__ void gemm_phase(PG8_LAS unsigned char* lds, const Gemm g, const Sched& S, const Epi& E, int tid_in) {
;     ...
;         for (int t = 0; t < nt; t += 2) {
;             const bool last = (t == nt - 2);
;             const char* a1 = cA + (size_t)(t + 1) * kstep;
;             const char* a2 = last ? nA : cA + (size_t)(t + 2) * kstep; const char* b2 = last ? nB : cB + (size_t)(t + 2) * kstep;
;             const char* a3 = a2 + kstep; const char* b3 = b2 + kstep;
;     ...
;             PG8_LDB(B0, 1, 0); PG8_LDB(B1, 1, 1); PG8_SCHED; PG8_LDA(At, 1, 0); PG8_STAGE(PG8_SA(0, 1), a2 + hstep, voffA);
;             PG8_WAIT_V(8); PG8_WAIT_L(0); PG8_BAR; PG8_MMA(0, 0, At, B0); PG8_MMA(0, 1, At, B1); PG8_BAR; PG8_SCHED;
;             PG8_LDA(At, 1, 1); PG8_STAGE(PG8_SB(1, 0), b3, voffB); PG8_STAGE(PG8_SB(1, 1), b3 + hstep, voffB); PG8_STAGE(PG8_SA(1, 0), a3, voffA);
;             PG8_WAIT_V(8); PG8_WAIT_L(0); PG8_BAR; PG8_MMA(1, 0, At, B0); PG8_MMA(1, 1, At, B1); PG8_BAR; PG8_SCHED;
	s_setprio 1
	ds_read_b128 v[192:195], v173 offset:49152
	ds_read_b128 v[196:199], v173 offset:50176
	ds_read_b128 v[200:203], v173 offset:51200
	ds_read_b128 v[204:207], v173 offset:52224
	ds_read_b128 v[208:211], v175 offset:32768
	ds_read_b128 v[212:215], v175 offset:33792
	ds_read_b128 v[216:219], v175 offset:34816
	ds_read_b128 v[220:223], v175 offset:35840
	ds_read_b128 v[224:227], v175 offset:36864
	ds_read_b128 v[228:231], v175 offset:37888
	ds_read_b128 v[232:235], v175 offset:38912
	ds_read_b128 v[236:239], v175 offset:39936
	s_add_i32 m0, s14, 0x4000
	s_add_u32 s100, s16, 0x80000
	s_addc_u32 s101, s17, 0
	global_load_lds_dwordx4 v148, s[100:101]
	s_add_i32 m0, s14, 0x6000
	s_nop 0
	global_load_lds_dwordx4 v146, s[100:101]
	s_add_i32 m0, s14, 0x18000
	s_add_u32 s100, s18, 0x80
	s_addc_u32 s101, s19, 0
	global_load_lds_dwordx4 v128, s[100:101]
	s_add_i32 m0, s14, 0x1a000
	s_nop 0
	global_load_lds_dwordx4 v144, s[100:101]
	s_setprio 0
	s_waitcnt vmcnt(8) lgkmcnt(0)
	s_barrier
	v_mfma_f32_16x16x32_bf16 v[124:127], v[240:243], v[208:211], v[124:127]
	v_mfma_f32_16x16x32_bf16 v[116:119], v[248:251], v[208:211], v[116:119]
	v_mfma_f32_16x16x32_bf16 v[108:111], v[240:243], v[216:219], v[108:111]
	v_mfma_f32_16x16x32_bf16 v[100:103], v[248:251], v[216:219], v[100:103]
	v_mfma_f32_16x16x32_bf16 v[92:95], v[240:243], v[224:227], v[92:95]
	v_mfma_f32_16x16x32_bf16 v[84:87], v[248:251], v[224:227], v[84:87]
	v_mfma_f32_16x16x32_bf16 v[76:79], v[240:243], v[232:235], v[76:79]
	v_mfma_f32_16x16x32_bf16 v[68:71], v[248:251], v[232:235], v[68:71]
	v_mfma_f32_16x16x32_bf16 v[124:127], v[244:247], v[212:215], v[124:127]
	v_mfma_f32_16x16x32_bf16 v[116:119], v[164:167], v[212:215], v[116:119]
	v_mfma_f32_16x16x32_bf16 v[108:111], v[244:247], v[220:223], v[108:111]
	v_mfma_f32_16x16x32_bf16 v[100:103], v[164:167], v[220:223], v[100:103]
	v_mfma_f32_16x16x32_bf16 v[92:95], v[244:247], v[228:231], v[92:95]
	v_mfma_f32_16x16x32_bf16 v[84:87], v[164:167], v[228:231], v[84:87]
	v_mfma_f32_16x16x32_bf16 v[76:79], v[244:247], v[236:239], v[76:79]
	v_mfma_f32_16x16x32_bf16 v[68:71], v[164:167], v[236:239], v[68:71]
	v_mfma_f32_16x16x32_bf16 v[120:123], v[192:195], v[208:211], v[120:123]
	v_mfma_f32_16x16x32_bf16 v[112:115], v[200:203], v[208:211], v[112:115]
	v_mfma_f32_16x16x32_bf16 v[104:107], v[192:195], v[216:219], v[104:107]
	v_mfma_f32_16x16x32_bf16 v[96:99], v[200:203], v[216:219], v[96:99]
	v_mfma_f32_16x16x32_bf16 v[88:91], v[192:195], v[224:227], v[88:91]
	v_mfma_f32_16x16x32_bf16 v[80:83], v[200:203], v[224:227], v[80:83]
	v_mfma_f32_16x16x32_bf16 v[72:75], v[192:195], v[232:235], v[72:75]
	v_mfma_f32_16x16x32_bf16 v[64:67], v[200:203], v[232:235], v[64:67]
	v_mfma_f32_16x16x32_bf16 v[120:123], v[196:199], v[212:215], v[120:123]
	v_mfma_f32_16x16x32_bf16 v[112:115], v[204:207], v[212:215], v[112:115]
	v_mfma_f32_16x16x32_bf16 v[104:107], v[196:199], v[220:223], v[104:107]
	v_mfma_f32_16x16x32_bf16 v[96:99], v[204:207], v[220:223], v[96:99]
	v_mfma_f32_16x16x32_bf16 v[88:91], v[196:199], v[228:231], v[88:91]
	v_mfma_f32_16x16x32_bf16 v[80:83], v[204:207], v[228:231], v[80:83]
	v_mfma_f32_16x16x32_bf16 v[72:75], v[196:199], v[236:239], v[72:75]
	v_mfma_f32_16x16x32_bf16 v[64:67], v[204:207], v[236:239], v[64:67]
	s_barrier
	s_setprio 1
	ds_read_b128 v[208:211], v175 offset:49152
	ds_read_b128 v[212:215], v175 offset:50176
	ds_read_b128 v[216:219], v175 offset:51200
	ds_read_b128 v[220:223], v175 offset:52224
	ds_read_b128 v[224:227], v175 offset:53248
	ds_read_b128 v[228:231], v175 offset:54272
	ds_read_b128 v[232:235], v175 offset:55296
	ds_read_b128 v[236:239], v175 offset:56320
	ds_read_b128 v[176:179], v173
	ds_read_b128 v[180:183], v173 offset:1024
	ds_read_b128 v[184:187], v173 offset:2048
	ds_read_b128 v[188:191], v173 offset:3072
	s_add_i32 m0, s14, 0x1c000
	s_add_u32 s100, s18, 0x80080
	s_addc_u32 s101, s19, 0
	global_load_lds_dwordx4 v128, s[100:101]
	s_add_i32 m0, s14, 0x1e000
	s_nop 0
	global_load_lds_dwordx4 v144, s[100:101]
	s_add_i32 m0, s14, 0x8000
	s_add_u32 s100, s16, 0x80
	s_addc_u32 s101, s17, 0
	global_load_lds_dwordx4 v148, s[100:101]
	s_add_i32 m0, s14, 0xa000
	s_nop 0
	global_load_lds_dwordx4 v146, s[100:101]
	s_add_u32 s16, s16, 0x100
	s_addc_u32 s17, s17, 0
	s_add_u32 s18, s18, 0x100
	s_addc_u32 s19, s19, 0
	s_add_u32 s100, s16, 0x7ff80
	s_addc_u32 s101, s17, 0
	v_readfirstlane_b32 s15, v160
	v_readfirstlane_b32 s1, v131
	v_readfirstlane_b32 s3, v162
	v_readfirstlane_b32 s11, v161
	s_cmp_eq_u32 s2, 26
	s_cselect_b32 s16, s15, s16
	s_cselect_b32 s17, s1, s17
	s_cselect_b32 s18, s3, s18
	s_cselect_b32 s19, s11, s19
	s_setprio 0
	s_waitcnt vmcnt(8) lgkmcnt(0)
	s_barrier
	v_mfma_f32_16x16x32_bf16 v[60:63], v[240:243], v[208:211], v[60:63]
	v_mfma_f32_16x16x32_bf16 v[52:55], v[248:251], v[208:211], v[52:55]
	v_mfma_f32_16x16x32_bf16 v[44:47], v[240:243], v[216:219], v[44:47]
	v_mfma_f32_16x16x32_bf16 v[36:39], v[248:251], v[216:219], v[36:39]
	v_mfma_f32_16x16x32_bf16 v[28:31], v[240:243], v[224:227], v[28:31]
	v_mfma_f32_16x16x32_bf16 v[20:23], v[248:251], v[224:227], v[20:23]
	v_mfma_f32_16x16x32_bf16 v[12:15], v[240:243], v[232:235], v[12:15]
	v_mfma_f32_16x16x32_bf16 v[4:7], v[248:251], v[232:235], v[4:7]
	v_mfma_f32_16x16x32_bf16 v[60:63], v[244:247], v[212:215], v[60:63]
	v_mfma_f32_16x16x32_bf16 v[52:55], v[164:167], v[212:215], v[52:55]
	v_mfma_f32_16x16x32_bf16 v[44:47], v[244:247], v[220:223], v[44:47]
	v_mfma_f32_16x16x32_bf16 v[36:39], v[164:167], v[220:223], v[36:39]
	v_mfma_f32_16x16x32_bf16 v[28:31], v[244:247], v[228:231], v[28:31]
	v_mfma_f32_16x16x32_bf16 v[20:23], v[164:167], v[228:231], v[20:23]
	v_mfma_f32_16x16x32_bf16 v[12:15], v[244:247], v[236:239], v[12:15]
	v_mfma_f32_16x16x32_bf16 v[4:7], v[164:167], v[236:239], v[4:7]
	v_mfma_f32_16x16x32_bf16 v[56:59], v[192:195], v[208:211], v[56:59]
	v_mfma_f32_16x16x32_bf16 v[48:51], v[200:203], v[208:211], v[48:51]
	v_mfma_f32_16x16x32_bf16 v[40:43], v[192:195], v[216:219], v[40:43]
	v_mfma_f32_16x16x32_bf16 v[32:35], v[200:203], v[216:219], v[32:35]
	v_mfma_f32_16x16x32_bf16 v[24:27], v[192:195], v[224:227], v[24:27]
	v_mfma_f32_16x16x32_bf16 v[16:19], v[200:203], v[224:227], v[16:19]
	v_mfma_f32_16x16x32_bf16 v[8:11], v[192:195], v[232:235], v[8:11]
	v_mfma_f32_16x16x32_bf16 v[0:3], v[200:203], v[232:235], v[0:3]
	v_mfma_f32_16x16x32_bf16 v[56:59], v[196:199], v[212:215], v[56:59]
	v_mfma_f32_16x16x32_bf16 v[48:51], v[204:207], v[212:215], v[48:51]
	v_mfma_f32_16x16x32_bf16 v[40:43], v[196:199], v[220:223], v[40:43]
	v_mfma_f32_16x16x32_bf16 v[32:35], v[204:207], v[220:223], v[32:35]
	v_mfma_f32_16x16x32_bf16 v[24:27], v[196:199], v[228:231], v[24:27]
	v_mfma_f32_16x16x32_bf16 v[16:19], v[204:207], v[228:231], v[16:19]
	v_mfma_f32_16x16x32_bf16 v[8:11], v[196:199], v[236:239], v[8:11]
	v_mfma_f32_16x16x32_bf16 v[0:3], v[204:207], v[236:239], v[0:3]
	s_barrier
	s_setprio 1
	s_add_i32 s2, s2, 2
	s_cmp_gt_u32 s2, 29
	s_cbranch_scc0 .LBB0_588
	s_setprio 0
	s_and_b64 vcc, exec, s[8:9]
	s_cbranch_vccz .LBB0_591
	s_barrier
